# non-temporal hint on the GEMM-1 and out-GEMM output stores so the streamed outputs do not evict the L2-resident weight panels
# speedup vs baseline: 1.0139x; 1.0002x over previous
; DEV int bid_() { int b = blockIdx.x; asm volatile("" : "+s"(b)); return b; }
; __device__ void phase_gemm1(PRef p, bf16* sA, bf16* sB) {
;   const int xcd_ = bid_() & 7, per_ = gridDim.x >> 3;
;   for (int t = bid_() >> 3; t < 36 * 24; t += per_) {
;     int rt = xcd_ + 8 * (t / 24), ct = t % 24;
;     f32x16 acc[2][2];
;     zero_acc<2>(acc);
;     gemm_tile<2>(acc, p.HY + (size_t)rt * 128 * 1024, 1024, p.WT1 + (size_t)ct * 128 * 1024, 1024, 1024, sA, sB);
;     bf16* dst;
;     int ld, c0;
;     if (ct < 14) { dst = p.ZA; ld = 1792; c0 = ct * 128; }
;     else if (ct < 18) { dst = p.ZB; ld = 512; c0 = (ct - 14) * 128; }
;     else { dst = p.ZC; ld = 768; c0 = (ct - 18) * 128; }
;     stage_tile<2>(acc, sA);
;     TILE_CHUNKS(2, sA, { *(u32x4*)(dst + (size_t)(rt * 128 + trow) * ld + c0 + tcol) = cv; })
;   }
.LBB0_304:
	v_mov_b32_e32 v0, v196
	s_load_dwordx2 s[12:13], s[20:21], 0x0
	v_cvt_pk_bf16_f32 v52, v52, v53
	v_lshrrev_b32_e32 v1, 1, v0
	v_and_b32_e32 v2, 31, v0
	v_and_or_b32 v1, v1, s75, v2
	v_and_b32_e32 v2, 64, v0
	v_lshrrev_b32_e32 v0, 2, v0
	v_and_b32_e32 v0, 8, v0
	v_lshl_or_b32 v0, v2, 1, v0
	v_mad_u64_u32 v[0:1], s[0:1], v1, s52, v[0:1]
	v_cvt_pk_bf16_f32 v53, v54, v55
	v_cvt_pk_bf16_f32 v54, v56, v57
	v_cvt_pk_bf16_f32 v55, v58, v59
	v_cvt_pk_bf16_f32 v36, v36, v37
	v_cvt_pk_bf16_f32 v37, v38, v39
	v_cvt_pk_bf16_f32 v38, v40, v41
	v_cvt_pk_bf16_f32 v39, v42, v43
	s_waitcnt lgkmcnt(0)
	s_barrier
	ds_write2_b64 v0, v[52:53], v[54:55] offset1:2
	v_cvt_pk_bf16_f32 v52, v60, v61
	v_cvt_pk_bf16_f32 v53, v62, v63
	v_cvt_pk_bf16_f32 v54, v64, v65
	v_cvt_pk_bf16_f32 v55, v66, v67
	ds_write2_b64 v0, v[36:37], v[38:39] offset0:8 offset1:10
	v_cvt_pk_bf16_f32 v36, v44, v45
	v_cvt_pk_bf16_f32 v37, v46, v47
	v_cvt_pk_bf16_f32 v38, v48, v49
	v_cvt_pk_bf16_f32 v39, v50, v51
	v_cvt_pk_bf16_f32 v20, v20, v21
	v_cvt_pk_bf16_f32 v21, v22, v23
	v_cvt_pk_bf16_f32 v22, v24, v25
	v_cvt_pk_bf16_f32 v23, v26, v27
	v_add_u32_e32 v2, 0x2000, v0
	ds_write2_b64 v0, v[52:53], v[54:55] offset0:4 offset1:6
	ds_write2_b64 v0, v[36:37], v[38:39] offset0:12 offset1:14
	ds_write2_b64 v2, v[20:21], v[22:23] offset0:64 offset1:66
	v_cvt_pk_bf16_f32 v0, v28, v29
	v_cvt_pk_bf16_f32 v1, v30, v31
	v_cvt_pk_bf16_f32 v20, v32, v33
	v_cvt_pk_bf16_f32 v21, v34, v35
	ds_write2_b64 v2, v[0:1], v[20:21] offset0:68 offset1:70
	v_cvt_pk_bf16_f32 v0, v4, v5
	v_cvt_pk_bf16_f32 v1, v6, v7
	v_cvt_pk_bf16_f32 v4, v8, v9
	v_cvt_pk_bf16_f32 v5, v10, v11
	ds_write2_b64 v2, v[0:1], v[4:5] offset0:72 offset1:74
	v_cvt_pk_bf16_f32 v0, v12, v13
	v_cvt_pk_bf16_f32 v1, v14, v15
	v_cvt_pk_bf16_f32 v4, v16, v17
	v_cvt_pk_bf16_f32 v5, v18, v19
	ds_write2_b64 v2, v[0:1], v[4:5] offset0:76 offset1:78
	v_mov_b32_e32 v2, v196
	s_waitcnt lgkmcnt(0)
	s_barrier
	s_lshl_b32 s20, s10, 7
	s_ashr_i32 s19, s18, 31
	s_lshl_b64 s[0:1], s[18:19], 1
	s_add_u32 s10, s12, s0
	s_addc_u32 s11, s13, s1
	s_mul_hi_u32 s1, s20, s14
	s_mul_i32 s0, s20, s14
	s_lshl_b64 s[0:1], s[0:1], 1
	s_add_u32 s98, s10, s0
	s_addc_u32 s99, s11, s1
	s_lshl_b32 s1, s14, 5
	v_lshrrev_b32_e32 v60, 4, v196
	v_and_b32_e32 v61, 15, v196
	v_mul_lo_u32 v62, v60, s52
	v_lshl_add_u32 v62, v61, 4, v62
	v_mul_lo_u32 v63, v60, s14
	v_lshlrev_b32_e32 v63, 1, v63
	v_lshl_add_u32 v63, v61, 4, v63
	ds_read_b128 v[20:23], v62 offset:0
	ds_read_b128 v[24:27], v62 offset:4352
	ds_read_b128 v[28:31], v62 offset:8704
	ds_read_b128 v[32:35], v62 offset:13056
	ds_read_b128 v[36:39], v62 offset:17408
	ds_read_b128 v[40:43], v62 offset:21760
	ds_read_b128 v[44:47], v62 offset:26112
	ds_read_b128 v[48:51], v62 offset:30464
	s_waitcnt lgkmcnt(7)
	global_store_dwordx4 v63, v[20:23], s[98:99] nt
	s_add_u32 s98, s98, s1
	s_addc_u32 s99, s99, 0
	s_waitcnt lgkmcnt(6)
	global_store_dwordx4 v63, v[24:27], s[98:99] nt
	s_add_u32 s98, s98, s1
	s_addc_u32 s99, s99, 0
	s_waitcnt lgkmcnt(5)
	global_store_dwordx4 v63, v[28:31], s[98:99] nt
	s_add_u32 s98, s98, s1
	s_addc_u32 s99, s99, 0
	s_waitcnt lgkmcnt(4)
	global_store_dwordx4 v63, v[32:35], s[98:99] nt
	s_add_u32 s98, s98, s1
	s_addc_u32 s99, s99, 0
	s_waitcnt lgkmcnt(3)
	global_store_dwordx4 v63, v[36:39], s[98:99] nt
	s_add_u32 s98, s98, s1
	s_addc_u32 s99, s99, 0
	s_waitcnt lgkmcnt(2)
	global_store_dwordx4 v63, v[40:43], s[98:99] nt
	s_add_u32 s98, s98, s1
	s_addc_u32 s99, s99, 0
	s_waitcnt lgkmcnt(1)
	global_store_dwordx4 v63, v[44:47], s[98:99] nt
	s_add_u32 s98, s98, s1
	s_addc_u32 s99, s99, 0
	s_waitcnt lgkmcnt(0)
	global_store_dwordx4 v63, v[48:51], s[98:99] nt
	s_add_i32 s24, s24, s81
	s_movk_i32 s0, 0x360
	s_cmp_eq_u32 s36, 0
	s_cselect_b32 s0, s0, 0x338
	s_cmp_lt_i32 s24, s0
	s_cbranch_scc0 .LBB0_319

; template <int NI>
; DEV void stage_tile(const f32x16 (&acc)[2][NI], bf16* sC) {
;     ...
;   __syncthreads();
; #pragma unroll
;   for (int mi = 0; mi < 2; mi++)
; #pragma unroll
;     for (int ni = 0; ni < NI; ni++)
; #pragma unroll
;       for (int g = 0; g < 4; g++) {
;         int row = wm * 64 + mi * 32 + (lane & 31);
;         int col = wn * NI * 32 + ni * 32 + 8 * g + 4 * (lane >> 5);
;         uint2 v;
;         v.x = pack2(acc[mi][ni][4 * g], acc[mi][ni][4 * g + 1]);
;         v.y = pack2(acc[mi][ni][4 * g + 2], acc[mi][ni][4 * g + 3]);
;         *(uint2*)(sC + row * LDC + col) = v;
;       }
;   __syncthreads();
.LBB0_1089:
	v_mov_b32_e32 v0, v196
	s_nop 5
	v_cvt_pk_bf16_f32 v52, v52, v53
	v_lshrrev_b32_e32 v1, 1, v0
	v_and_b32_e32 v2, 31, v0
	v_and_or_b32 v1, v1, s75, v2
	v_and_b32_e32 v2, 64, v0
	v_lshrrev_b32_e32 v0, 2, v0
	v_and_b32_e32 v0, 8, v0
	v_lshl_or_b32 v0, v2, 1, v0
	v_mad_u64_u32 v[0:1], s[14:15], v1, s52, v[0:1]
	v_cvt_pk_bf16_f32 v53, v54, v55
	v_cvt_pk_bf16_f32 v54, v56, v57
	v_cvt_pk_bf16_f32 v55, v58, v59
	v_cvt_pk_bf16_f32 v36, v36, v37
	v_cvt_pk_bf16_f32 v37, v38, v39
	v_cvt_pk_bf16_f32 v38, v40, v41
	v_cvt_pk_bf16_f32 v39, v42, v43
	s_barrier
	ds_write2_b64 v0, v[52:53], v[54:55] offset1:2
	v_cvt_pk_bf16_f32 v52, v60, v61
	v_cvt_pk_bf16_f32 v53, v62, v63
	v_cvt_pk_bf16_f32 v54, v64, v65
	v_cvt_pk_bf16_f32 v55, v66, v67
	ds_write2_b64 v0, v[36:37], v[38:39] offset0:8 offset1:10
	v_cvt_pk_bf16_f32 v36, v44, v45
	v_cvt_pk_bf16_f32 v37, v46, v47
	v_cvt_pk_bf16_f32 v38, v48, v49
	v_cvt_pk_bf16_f32 v39, v50, v51
	v_cvt_pk_bf16_f32 v20, v20, v21
	v_cvt_pk_bf16_f32 v21, v22, v23
	v_cvt_pk_bf16_f32 v22, v24, v25
	v_cvt_pk_bf16_f32 v23, v26, v27
	v_add_u32_e32 v2, 0x2000, v0
	ds_write2_b64 v0, v[52:53], v[54:55] offset0:4 offset1:6
	ds_write2_b64 v0, v[36:37], v[38:39] offset0:12 offset1:14
	ds_write2_b64 v2, v[20:21], v[22:23] offset0:64 offset1:66
	v_cvt_pk_bf16_f32 v0, v28, v29
	v_cvt_pk_bf16_f32 v1, v30, v31
	v_cvt_pk_bf16_f32 v20, v32, v33
	v_cvt_pk_bf16_f32 v21, v34, v35
	ds_write2_b64 v2, v[0:1], v[20:21] offset0:68 offset1:70
	v_cvt_pk_bf16_f32 v0, v4, v5
	v_cvt_pk_bf16_f32 v1, v6, v7
	v_cvt_pk_bf16_f32 v4, v8, v9
	v_cvt_pk_bf16_f32 v5, v10, v11
	ds_write2_b64 v2, v[0:1], v[4:5] offset0:72 offset1:74
	v_cvt_pk_bf16_f32 v0, v12, v13
	v_cvt_pk_bf16_f32 v1, v14, v15
	v_cvt_pk_bf16_f32 v4, v16, v17
	v_cvt_pk_bf16_f32 v5, v18, v19
	ds_write2_b64 v2, v[0:1], v[4:5] offset0:76 offset1:78
	v_mov_b32_e32 v2, v196
	s_waitcnt lgkmcnt(0)
	s_barrier
; __device__ void phase_out(PRef p, int l, const bf16* M, const float* xl, const float* xc, bf16* sA, bf16* sB) {
;     ...
;     int b = rt / 18;
;     bool isctx = (rt % 18) < 2;
;     const float* gate = p.MOD + ((size_t)l * 17 + (isctx ? 16 : b)) * 3072 + 2048;
;     stage_tile<2>(acc, sA);
;     TILE_CHUNKS(2, sA, {
;       int R = rt * 128 + trow;
;       int col = ct * 128 + tcol;
;       int tp = R % TPB;
;       const float* xin;
;       float* dstp;
;       if (isctx) {
;         xin = xc + ((size_t)b * 256 + tp) * 1024 + col;
;         dstp = p.XC + ((size_t)b * 256 + tp) * 1024 + col;
;       } else {
;         xin = xl + ((size_t)b * 2048 + (tp - 256)) * 1024 + col;
;         dstp = p.out + ((size_t)b * 2048 + (tp - 256)) * 1024 + col;
;       }
;       f32x4v x0 = *(const f32x4v*)xin, x1 = *(const f32x4v*)(xin + 4);
;       f32x4v g0 = *(const f32x4v*)(gate + col), g1 = *(const f32x4v*)(gate + col + 4);
;       f32x4v o0, o1;
;       o0.x = x0.x + g0.x * __uint_as_float(cv[0] << 16);
;       o0.y = x0.y + g0.y * __uint_as_float(cv[0] & 0xffff0000u);
;       o0.z = x0.z + g0.z * __uint_as_float(cv[1] << 16);
;       o0.w = x0.w + g0.w * __uint_as_float(cv[1] & 0xffff0000u);
;       o1.x = x1.x + g1.x * __uint_as_float(cv[2] << 16);
;       o1.y = x1.y + g1.y * __uint_as_float(cv[2] & 0xffff0000u);
;       o1.z = x1.z + g1.z * __uint_as_float(cv[3] << 16);
;       o1.w = x1.w + g1.w * __uint_as_float(cv[3] & 0xffff0000u);
;       *(f32x4v*)dstp = o0;
;       *(f32x4v*)(dstp + 4) = o1;
;     })
	s_lshl_b32 s14, s20, 9
	s_and_b64 s[22:23], s[22:23], exec
	s_cselect_b32 s18, 16, s18
	s_ashr_i32 s19, s18, 31
	s_add_u32 s18, s8, s18
	s_addc_u32 s19, s9, s19
	s_mulk_i32 s19, 0x3000
	s_mul_hi_u32 s21, s18, 0x3000
	s_add_i32 s21, s21, s19
	s_mulk_i32 s18, 0x3000
	s_add_u32 s18, s76, s18
	s_addc_u32 s19, s77, s21
	s_add_u32 s18, s18, 0x2000
	s_addc_u32 s19, s19, 0
	s_add_u32 s18, s18, s14
	s_addc_u32 s19, s19, 0
	v_lshrrev_b32_e32 v92, 4, v196
	v_and_b32_e32 v93, 15, v196
	v_mul_lo_u32 v94, v92, s52
	v_lshl_add_u32 v94, v93, 4, v94
	v_lshlrev_b32_e32 v93, 5, v93
	global_load_dwordx4 v[84:87], v93, s[18:19]
	global_load_dwordx4 v[88:91], v93, s[18:19] offset:16
	ds_read_b128 v[4:7], v94 offset:0
	s_waitcnt vmcnt(0) lgkmcnt(0)
	v_lshlrev_b32_e32 v8, 16, v4
	v_and_b32_e32 v9, 0xffff0000, v4
	v_lshlrev_b32_e32 v10, 16, v5
	v_and_b32_e32 v11, 0xffff0000, v5
	v_lshlrev_b32_e32 v12, 16, v6
	v_and_b32_e32 v13, 0xffff0000, v6
	v_lshlrev_b32_e32 v14, 16, v7
	v_and_b32_e32 v15, 0xffff0000, v7
	v_fmac_f32_e32 v162, v84, v8
	v_fmac_f32_e32 v163, v85, v9
	v_fmac_f32_e32 v164, v86, v10
	v_fmac_f32_e32 v165, v87, v11
	v_fmac_f32_e32 v166, v88, v12
	v_fmac_f32_e32 v167, v89, v13
	v_fmac_f32_e32 v168, v90, v14
	v_fmac_f32_e32 v169, v91, v15
	global_store_dwordx4 v242, v[162:165], s[26:27] nt
	global_store_dwordx4 v242, v[166:169], s[26:27] offset:16 nt
	s_add_u32 s26, s26, 0x10000
	s_addc_u32 s27, s27, 0
	ds_read_b128 v[4:7], v94 offset:4352
	s_waitcnt lgkmcnt(0)
	v_lshlrev_b32_e32 v8, 16, v4
	v_and_b32_e32 v9, 0xffff0000, v4
	v_lshlrev_b32_e32 v10, 16, v5
	v_and_b32_e32 v11, 0xffff0000, v5
	v_lshlrev_b32_e32 v12, 16, v6
	v_and_b32_e32 v13, 0xffff0000, v6
	v_lshlrev_b32_e32 v14, 16, v7
	v_and_b32_e32 v15, 0xffff0000, v7
	v_fmac_f32_e32 v170, v84, v8
	v_fmac_f32_e32 v171, v85, v9
	v_fmac_f32_e32 v172, v86, v10
	v_fmac_f32_e32 v173, v87, v11
	v_fmac_f32_e32 v174, v88, v12
	v_fmac_f32_e32 v175, v89, v13
	v_fmac_f32_e32 v176, v90, v14
	v_fmac_f32_e32 v177, v91, v15
	global_store_dwordx4 v242, v[170:173], s[26:27] nt
	global_store_dwordx4 v242, v[174:177], s[26:27] offset:16 nt
	s_add_u32 s26, s26, 0x10000
	s_addc_u32 s27, s27, 0
	ds_read_b128 v[4:7], v94 offset:8704
	s_waitcnt lgkmcnt(0)
	v_lshlrev_b32_e32 v8, 16, v4
	v_and_b32_e32 v9, 0xffff0000, v4
	v_lshlrev_b32_e32 v10, 16, v5
	v_and_b32_e32 v11, 0xffff0000, v5
	v_lshlrev_b32_e32 v12, 16, v6
	v_and_b32_e32 v13, 0xffff0000, v6
	v_lshlrev_b32_e32 v14, 16, v7
	v_and_b32_e32 v15, 0xffff0000, v7
	v_fmac_f32_e32 v178, v84, v8
	v_fmac_f32_e32 v179, v85, v9
	v_fmac_f32_e32 v180, v86, v10
	v_fmac_f32_e32 v181, v87, v11
	v_fmac_f32_e32 v182, v88, v12
	v_fmac_f32_e32 v183, v89, v13
	v_fmac_f32_e32 v184, v90, v14
	v_fmac_f32_e32 v185, v91, v15
	global_store_dwordx4 v242, v[178:181], s[26:27] nt
	global_store_dwordx4 v242, v[182:185], s[26:27] offset:16 nt
	s_add_u32 s26, s26, 0x10000
	s_addc_u32 s27, s27, 0
	ds_read_b128 v[4:7], v94 offset:13056
	s_waitcnt lgkmcnt(0)
	v_lshlrev_b32_e32 v8, 16, v4
	v_and_b32_e32 v9, 0xffff0000, v4
	v_lshlrev_b32_e32 v10, 16, v5
	v_and_b32_e32 v11, 0xffff0000, v5
	v_lshlrev_b32_e32 v12, 16, v6
	v_and_b32_e32 v13, 0xffff0000, v6
	v_lshlrev_b32_e32 v14, 16, v7
	v_and_b32_e32 v15, 0xffff0000, v7
	v_fmac_f32_e32 v186, v84, v8
	v_fmac_f32_e32 v187, v85, v9
	v_fmac_f32_e32 v188, v86, v10
	v_fmac_f32_e32 v189, v87, v11
	v_fmac_f32_e32 v190, v88, v12
	v_fmac_f32_e32 v191, v89, v13
	v_fmac_f32_e32 v192, v90, v14
	v_fmac_f32_e32 v193, v91, v15
	global_store_dwordx4 v242, v[186:189], s[26:27] nt
	global_store_dwordx4 v242, v[190:193], s[26:27] offset:16 nt
	s_add_u32 s26, s26, 0x10000
	s_addc_u32 s27, s27, 0
	ds_read_b128 v[4:7], v94 offset:17408
	s_waitcnt lgkmcnt(0)
	v_lshlrev_b32_e32 v8, 16, v4
	v_and_b32_e32 v9, 0xffff0000, v4
	v_lshlrev_b32_e32 v10, 16, v5
	v_and_b32_e32 v11, 0xffff0000, v5
	v_lshlrev_b32_e32 v12, 16, v6
	v_and_b32_e32 v13, 0xffff0000, v6
	v_lshlrev_b32_e32 v14, 16, v7
	v_and_b32_e32 v15, 0xffff0000, v7
	v_fmac_f32_e32 v210, v84, v8
	v_fmac_f32_e32 v211, v85, v9
	v_fmac_f32_e32 v212, v86, v10
	v_fmac_f32_e32 v213, v87, v11
	v_fmac_f32_e32 v214, v88, v12
	v_fmac_f32_e32 v215, v89, v13
	v_fmac_f32_e32 v216, v90, v14
	v_fmac_f32_e32 v217, v91, v15
	global_store_dwordx4 v242, v[210:213], s[26:27] nt
	global_store_dwordx4 v242, v[214:217], s[26:27] offset:16 nt
	s_add_u32 s26, s26, 0x10000
	s_addc_u32 s27, s27, 0
	ds_read_b128 v[4:7], v94 offset:21760
	s_waitcnt lgkmcnt(0)
	v_lshlrev_b32_e32 v8, 16, v4
	v_and_b32_e32 v9, 0xffff0000, v4
	v_lshlrev_b32_e32 v10, 16, v5
	v_and_b32_e32 v11, 0xffff0000, v5
	v_lshlrev_b32_e32 v12, 16, v6
	v_and_b32_e32 v13, 0xffff0000, v6
	v_lshlrev_b32_e32 v14, 16, v7
	v_and_b32_e32 v15, 0xffff0000, v7
	v_fmac_f32_e32 v218, v84, v8
	v_fmac_f32_e32 v219, v85, v9
	v_fmac_f32_e32 v220, v86, v10
	v_fmac_f32_e32 v221, v87, v11
	v_fmac_f32_e32 v222, v88, v12
	v_fmac_f32_e32 v223, v89, v13
	v_fmac_f32_e32 v224, v90, v14
	v_fmac_f32_e32 v225, v91, v15
	global_store_dwordx4 v242, v[218:221], s[26:27] nt
	global_store_dwordx4 v242, v[222:225], s[26:27] offset:16 nt
	s_add_u32 s26, s26, 0x10000
	s_addc_u32 s27, s27, 0
	ds_read_b128 v[4:7], v94 offset:26112
	s_waitcnt lgkmcnt(0)
	v_lshlrev_b32_e32 v8, 16, v4
	v_and_b32_e32 v9, 0xffff0000, v4
	v_lshlrev_b32_e32 v10, 16, v5
	v_and_b32_e32 v11, 0xffff0000, v5
	v_lshlrev_b32_e32 v12, 16, v6
	v_and_b32_e32 v13, 0xffff0000, v6
	v_lshlrev_b32_e32 v14, 16, v7
	v_and_b32_e32 v15, 0xffff0000, v7
	v_fmac_f32_e32 v226, v84, v8
	v_fmac_f32_e32 v227, v85, v9
	v_fmac_f32_e32 v228, v86, v10
	v_fmac_f32_e32 v229, v87, v11
	v_fmac_f32_e32 v230, v88, v12
	v_fmac_f32_e32 v231, v89, v13
	v_fmac_f32_e32 v232, v90, v14
	v_fmac_f32_e32 v233, v91, v15
	global_store_dwordx4 v242, v[226:229], s[26:27] nt
	global_store_dwordx4 v242, v[230:233], s[26:27] offset:16 nt
	s_add_u32 s26, s26, 0x10000
	s_addc_u32 s27, s27, 0
	ds_read_b128 v[4:7], v94 offset:30464
	s_waitcnt lgkmcnt(0)
	v_lshlrev_b32_e32 v8, 16, v4
	v_and_b32_e32 v9, 0xffff0000, v4
	v_lshlrev_b32_e32 v10, 16, v5
	v_and_b32_e32 v11, 0xffff0000, v5
	v_lshlrev_b32_e32 v12, 16, v6
	v_and_b32_e32 v13, 0xffff0000, v6
	v_lshlrev_b32_e32 v14, 16, v7
	v_and_b32_e32 v15, 0xffff0000, v7
	v_fmac_f32_e32 v234, v84, v8
	v_fmac_f32_e32 v235, v85, v9
	v_fmac_f32_e32 v236, v86, v10
	v_fmac_f32_e32 v237, v87, v11
	v_fmac_f32_e32 v238, v88, v12
	v_fmac_f32_e32 v239, v89, v13
	v_fmac_f32_e32 v240, v90, v14
	v_fmac_f32_e32 v241, v91, v15
	global_store_dwordx4 v242, v[234:237], s[26:27] nt
	global_store_dwordx4 v242, v[238:241], s[26:27] offset:16 nt
	s_branch .LBB0_1081
